# v7 plus the it=0 diagonal tile of the SSD output stage rewritten the same way
# baseline (speedup 1.0000x reference)
.LBB0_1000:
	v_mul_u32_u24_e32 v150, 0x120, v158
	v_add_u32_e32 v142, s83, v2
	v_add_u32_e32 v97, v142, v150
	ds_read_b128 v[24:27], v97
	ds_read_b128 v[144:147], v97 offset:32
	ds_read_b128 v[152:155], v97 offset:64
	s_lshl_b32 s6, s3, 9
	s_add_i32 s13, s6, 0
	s_add_i32 s13, s13, 0x23000
	v_lshl_add_u32 v163, v158, 2, s13
	v_lshlrev_b32_e32 v160, 2, v119
	v_cmp_le_u32_e32 vcc, v160, v158
	s_waitcnt lgkmcnt(2)
	v_mfma_f32_32x32x16_bf16 v[20:35], v[24:27], v[20:23], 0
	s_waitcnt lgkmcnt(1)
	v_mfma_f32_32x32x16_bf16 v[20:35], v[144:147], v[88:91], v[20:35]
	s_waitcnt lgkmcnt(0)
	v_mfma_f32_32x32x16_bf16 v[20:35], v[152:155], v[92:95], v[20:35]
	ds_read_b128 v[88:91], v97 offset:96
	ds_read_b128 v[92:95], v97 offset:128
	s_waitcnt lgkmcnt(1)
	v_mfma_f32_32x32x16_bf16 v[20:35], v[88:91], v[80:83], v[20:35]
	s_waitcnt lgkmcnt(0)
	v_mfma_f32_32x32x16_bf16 v[20:35], v[92:95], v[84:87], v[20:35]
	ds_read_b128 v[80:83], v97 offset:160
	ds_read_b128 v[84:87], v97 offset:192
	s_waitcnt lgkmcnt(1)
	v_mfma_f32_32x32x16_bf16 v[20:35], v[80:83], v[72:75], v[20:35]
	ds_read_b32 v72, v163
	s_waitcnt lgkmcnt(1)
	v_mfma_f32_32x32x16_bf16 v[20:35], v[84:87], v[76:79], v[20:35]
	ds_read_b128 v[74:77], v97 offset:224
	s_waitcnt lgkmcnt(0)
	v_mfma_f32_32x32x16_bf16 v[20:35], v[74:77], v[68:71], v[20:35]
	v_lshl_add_u32 v209, v160, 2, s13
	ds_read_b128 v[220:223], v209
	ds_read_b128 v[224:227], v209 offset:32
	ds_read_b128 v[228:231], v209 offset:64
	ds_read_b128 v[232:235], v209 offset:96
	s_lshl_b32 s10, s3, 7
	v_sub_u32_e32 v208, v158, v160
	s_waitcnt lgkmcnt(0)
	v_sub_f32_e32 v220, v72, v220
	v_sub_f32_e32 v221, v72, v221
	v_sub_f32_e32 v222, v72, v222
	v_sub_f32_e32 v223, v72, v223
	v_sub_f32_e32 v224, v72, v224
	v_sub_f32_e32 v225, v72, v225
	v_sub_f32_e32 v226, v72, v226
	v_sub_f32_e32 v227, v72, v227
	v_sub_f32_e32 v228, v72, v228
	v_sub_f32_e32 v229, v72, v229
	v_sub_f32_e32 v230, v72, v230
	v_sub_f32_e32 v231, v72, v231
	v_sub_f32_e32 v232, v72, v232
	v_sub_f32_e32 v233, v72, v233
	v_sub_f32_e32 v234, v72, v234
	v_sub_f32_e32 v235, v72, v235
	v_exp_f32_e32 v220, v220
	v_exp_f32_e32 v221, v221
	v_exp_f32_e32 v222, v222
	v_exp_f32_e32 v223, v223
	v_exp_f32_e32 v224, v224
	v_exp_f32_e32 v225, v225
	v_exp_f32_e32 v226, v226
	v_exp_f32_e32 v227, v227
	v_exp_f32_e32 v228, v228
	v_exp_f32_e32 v229, v229
	v_exp_f32_e32 v230, v230
	v_exp_f32_e32 v231, v231
	v_exp_f32_e32 v232, v232
	v_exp_f32_e32 v233, v233
	v_exp_f32_e32 v234, v234
	v_exp_f32_e32 v235, v235
	v_cmp_le_i32_e32 vcc, 0, v208
	v_cmp_le_i32_e64 s[6:7], 1, v208
	s_nop 1
	v_cndmask_b32_e32 v220, 0, v220, vcc
	v_cndmask_b32_e64 v221, 0, v221, s[6:7]
	v_cmp_le_i32_e32 vcc, 2, v208
	v_cmp_le_i32_e64 s[6:7], 3, v208
	s_nop 1
	v_cndmask_b32_e32 v222, 0, v222, vcc
	v_cndmask_b32_e64 v223, 0, v223, s[6:7]
	v_cmp_le_i32_e32 vcc, 8, v208
	v_cmp_le_i32_e64 s[6:7], 9, v208
	s_nop 1
	v_cndmask_b32_e32 v224, 0, v224, vcc
	v_cndmask_b32_e64 v225, 0, v225, s[6:7]
	v_cmp_le_i32_e32 vcc, 10, v208
	v_cmp_le_i32_e64 s[6:7], 11, v208
	s_nop 1
	v_cndmask_b32_e32 v226, 0, v226, vcc
	v_cndmask_b32_e64 v227, 0, v227, s[6:7]
	v_cmp_le_i32_e32 vcc, 16, v208
	v_cmp_le_i32_e64 s[6:7], 17, v208
	s_nop 1
	v_cndmask_b32_e32 v228, 0, v228, vcc
	v_cndmask_b32_e64 v229, 0, v229, s[6:7]
	v_cmp_le_i32_e32 vcc, 18, v208
	v_cmp_le_i32_e64 s[6:7], 19, v208
	s_nop 1
	v_cndmask_b32_e32 v230, 0, v230, vcc
	v_cndmask_b32_e64 v231, 0, v231, s[6:7]
	v_cmp_le_i32_e32 vcc, 24, v208
	v_cmp_le_i32_e64 s[6:7], 25, v208
	s_nop 1
	v_cndmask_b32_e32 v232, 0, v232, vcc
	v_cndmask_b32_e64 v233, 0, v233, s[6:7]
	v_cmp_le_i32_e32 vcc, 26, v208
	v_cmp_le_i32_e64 s[6:7], 27, v208
	s_nop 1
	v_cndmask_b32_e32 v234, 0, v234, vcc
	v_cndmask_b32_e64 v235, 0, v235, s[6:7]
	v_mul_f32_e32 v220, v20, v220
	v_mul_f32_e32 v221, v21, v221
	v_mul_f32_e32 v222, v22, v222
	v_mul_f32_e32 v223, v23, v223
	v_mul_f32_e32 v224, v24, v224
	v_mul_f32_e32 v225, v25, v225
	v_mul_f32_e32 v226, v26, v226
	v_mul_f32_e32 v227, v27, v227
	v_mul_f32_e32 v228, v28, v228
	v_mul_f32_e32 v229, v29, v229
	v_mul_f32_e32 v230, v30, v230
	v_mul_f32_e32 v231, v31, v231
	v_mul_f32_e32 v232, v32, v232
	v_mul_f32_e32 v233, v33, v233
	v_mul_f32_e32 v234, v34, v234
	v_mul_f32_e32 v235, v35, v235
	v_exp_f32_e32 v34, v72
	s_lshl_b32 s12, s3, 6
	v_and_b32_e32 v151, 16, v100
	v_and_b32_e32 v153, 12, v118
	v_pk_mul_f32 v[18:19], v[18:19], v[34:35] op_sel_hi:[1,0]
	v_pk_mul_f32 v[16:17], v[16:17], v[34:35] op_sel_hi:[1,0]
	v_pk_mul_f32 v[14:15], v[14:15], v[34:35] op_sel_hi:[1,0]
	v_pk_mul_f32 v[12:13], v[12:13], v[34:35] op_sel_hi:[1,0]
	v_pk_mul_f32 v[10:11], v[10:11], v[34:35] op_sel_hi:[1,0]
	v_pk_mul_f32 v[8:9], v[8:9], v[34:35] op_sel_hi:[1,0]
	v_pk_mul_f32 v[6:7], v[6:7], v[34:35] op_sel_hi:[1,0]
	v_pk_mul_f32 v[4:5], v[4:5], v[34:35] op_sel_hi:[1,0]
	v_or3_b32 v35, v153, v151, s12
	v_bfe_u32 v152, v100, 2, 2
	v_lshrrev_b32_e32 v34, 3, v100
	v_or_b32_e32 v35, s14, v35
	v_lshl_add_u32 v143, v35, 1, 0
	v_and_or_b32 v144, v34, 4, v152
	v_cvt_pk_bf16_f32 v72, v224, v225
	v_cvt_pk_bf16_f32 v21, v230, v231
	v_mad_u32_u24 v30, v144, s33, v143
	v_cvt_pk_bf16_f32 v70, v220, v221
	v_cvt_pk_bf16_f32 v71, v222, v223
	v_cvt_pk_bf16_f32 v73, v226, v227
	v_cvt_pk_bf16_f32 v20, v228, v229
	v_cvt_pk_bf16_f32 v22, v232, v233
	v_cvt_pk_bf16_f32 v23, v234, v235
	ds_read_b64_tr_b16 v[24:25], v30
	ds_read_b64_tr_b16 v[26:27], v30 offset:4352
	ds_read_b64_tr_b16 v[28:29], v30 offset:8704
	ds_read_b64_tr_b16 v[30:31], v30 offset:13056
	s_waitcnt lgkmcnt(2)
	v_mfma_f32_32x32x16_bf16 v[4:19], v[24:27], v[70:73], v[4:19]
	s_lshl_b32 s7, s10, 2
	s_add_i32 s7, s7, 0
	v_lshl_add_u32 v35, v158, 2, s7
	v_add_u32_e32 v162, 0x23800, v35
	s_or_b32 s6, s14, s12
	v_or_b32_e32 v34, s6, v160
	v_mad_u32_u24 v145, v158, s33, 0
	s_waitcnt lgkmcnt(0)
	v_mfma_f32_32x32x16_bf16 v[4:19], v[28:31], v[20:23], v[4:19]
	ds_read_b32 v20, v162
	v_lshlrev_b32_e32 v159, 1, v34
	v_lshlrev_b32_e32 v32, 16, v120
	v_and_b32_e32 v33, 0xffff0000, v120
	s_lshl_b32 s6, s15, 9
	s_waitcnt lgkmcnt(0)
	v_div_scale_f32 v21, s[10:11], v20, v20, v101
	v_rcp_f32_e32 v22, v21
	s_add_i32 s6, s6, 0
	s_add_i32 s6, s6, 0x24000
	v_lshl_add_u32 v161, v158, 2, s6
	v_fma_f32 v23, -v21, v22, 1.0
	v_fmac_f32_e32 v22, v23, v22
	v_div_scale_f32 v23, vcc, v101, v20, v101
	v_mul_f32_e32 v24, v23, v22
	v_fma_f32 v25, -v21, v24, v23
	v_fmac_f32_e32 v24, v25, v22
	v_fma_f32 v21, -v21, v24, v23
	v_div_fmas_f32 v21, v21, v22, v24
	v_div_fixup_f32 v24, v21, v20, v101
	v_add_u32_e32 v20, v145, v159
	v_mul_f32_e32 v25, 0xbfb8aa3b, v32
	ds_read2_b64 v[26:29], v20 offset1:2
	ds_read2_b64 v[20:23], v20 offset0:4 offset1:6
	v_exp_f32_e32 v25, v25
	s_waitcnt lgkmcnt(1)
	v_lshlrev_b32_e32 v30, 16, v26
	v_and_b32_e32 v31, 0xffff0000, v26
	v_add_f32_e32 v25, 1.0, v25
	v_rcp_f32_e32 v34, v25
	v_pk_fma_f32 v[4:5], v[24:25], v[30:31], v[4:5] op_sel_hi:[0,1,1]
	v_mul_f32_e32 v25, 0xbfb8aa3b, v33
	v_exp_f32_e32 v25, v25
	v_lshlrev_b32_e32 v26, 16, v27
	v_and_b32_e32 v27, 0xffff0000, v27
	v_add_f32_e32 v25, 1.0, v25
	v_rcp_f32_e32 v35, v25
	s_nop 0
	v_pk_mul_f32 v[30:31], v[34:35], v[32:33]
	s_nop 0
	v_pk_mul_f32 v[118:119], v[30:31], v[4:5]
	v_lshlrev_b32_e32 v30, 16, v121
	v_mul_f32_e32 v25, 0xbfb8aa3b, v30
	v_exp_f32_e32 v25, v25
	v_and_b32_e32 v31, 0xffff0000, v121
	v_pk_mul_f32 v[4:5], v[118:119], v[118:119]
	v_add_f32_e32 v25, 1.0, v25
	v_rcp_f32_e32 v32, v25
	v_pk_fma_f32 v[6:7], v[24:25], v[26:27], v[6:7] op_sel_hi:[0,1,1]
	v_mul_f32_e32 v25, 0xbfb8aa3b, v31
	v_exp_f32_e32 v25, v25
	v_add_f32_e32 v4, v4, v5
	v_mov_b32_e32 v5, v0
	v_add_f32_e32 v25, 1.0, v25
	v_rcp_f32_e32 v33, v25
	v_lshlrev_b32_e32 v5, 2, v5
	v_bitop3_b32 v5, v5, s93, v252 bitop3:0x6c
	v_pk_mul_f32 v[26:27], v[32:33], v[30:31]
	v_lshlrev_b32_e32 v30, 16, v124
	v_mul_f32_e32 v25, 0xbfb8aa3b, v30
	v_exp_f32_e32 v25, v25
	v_pk_mul_f32 v[120:121], v[26:27], v[6:7]
	v_lshlrev_b32_e32 v26, 16, v28
	v_and_b32_e32 v27, 0xffff0000, v28
	v_and_b32_e32 v31, 0xffff0000, v124
	v_add_f32_e32 v25, 1.0, v25
	v_rcp_f32_e32 v32, v25
	v_pk_fma_f32 v[8:9], v[24:25], v[26:27], v[8:9] op_sel_hi:[0,1,1]
	v_mul_f32_e32 v25, 0xbfb8aa3b, v31
	v_exp_f32_e32 v25, v25
	v_lshlrev_b32_e32 v28, 16, v125
	v_pk_mul_f32 v[6:7], v[120:121], v[120:121]
	v_add_f32_e32 v25, 1.0, v25
	v_rcp_f32_e32 v33, v25
	v_mul_f32_e32 v25, 0xbfb8aa3b, v28
	v_exp_f32_e32 v25, v25
	v_add_f32_e32 v4, v6, v4
	v_pk_mul_f32 v[26:27], v[32:33], v[30:31]
	v_add_f32_e32 v4, v7, v4
	v_pk_mul_f32 v[122:123], v[26:27], v[8:9]
	v_lshlrev_b32_e32 v26, 16, v29
	v_and_b32_e32 v27, 0xffff0000, v29
	v_and_b32_e32 v29, 0xffff0000, v125
	v_add_f32_e32 v25, 1.0, v25
	v_rcp_f32_e32 v30, v25
	v_pk_fma_f32 v[10:11], v[24:25], v[26:27], v[10:11] op_sel_hi:[0,1,1]
	v_mul_f32_e32 v25, 0xbfb8aa3b, v29
	v_exp_f32_e32 v25, v25
	v_pk_mul_f32 v[8:9], v[122:123], v[122:123]
	v_add_f32_e32 v25, 1.0, v25
	v_rcp_f32_e32 v31, v25
	v_add_f32_e32 v4, v8, v4
	v_add_f32_e32 v4, v9, v4
	v_pk_mul_f32 v[26:27], v[30:31], v[28:29]
	v_lshlrev_b32_e32 v28, 16, v128
	v_pk_mul_f32 v[124:125], v[26:27], v[10:11]
	s_waitcnt lgkmcnt(0)
	v_lshlrev_b32_e32 v26, 16, v20
	v_and_b32_e32 v27, 0xffff0000, v20
	v_mul_f32_e32 v20, 0xbfb8aa3b, v28
	v_exp_f32_e32 v20, v20
	v_and_b32_e32 v29, 0xffff0000, v128
	v_pk_fma_f32 v[12:13], v[24:25], v[26:27], v[12:13] op_sel_hi:[0,1,1]
	v_pk_mul_f32 v[10:11], v[124:125], v[124:125]
	v_add_f32_e32 v20, 1.0, v20
	v_rcp_f32_e32 v30, v20
	v_mul_f32_e32 v20, 0xbfb8aa3b, v29
	v_exp_f32_e32 v20, v20
	v_add_f32_e32 v4, v10, v4
	v_add_f32_e32 v4, v11, v4
	v_add_f32_e32 v20, 1.0, v20
	v_rcp_f32_e32 v31, v20
	v_lshlrev_b32_e32 v20, 16, v21
	v_and_b32_e32 v21, 0xffff0000, v21
	v_pk_mul_f32 v[26:27], v[30:31], v[28:29]
	s_nop 0
	v_pk_mul_f32 v[126:127], v[26:27], v[12:13]
	v_lshlrev_b32_e32 v26, 16, v129
	v_mul_f32_e32 v25, 0xbfb8aa3b, v26
	v_exp_f32_e32 v25, v25
	v_and_b32_e32 v27, 0xffff0000, v129
	v_pk_mul_f32 v[12:13], v[126:127], v[126:127]
	v_add_f32_e32 v25, 1.0, v25
	v_pk_fma_f32 v[14:15], v[24:25], v[20:21], v[14:15] op_sel_hi:[0,1,1]
	v_mul_f32_e32 v20, 0xbfb8aa3b, v27
	v_exp_f32_e32 v20, v20
	v_rcp_f32_e32 v28, v25
	v_add_f32_e32 v4, v12, v4
	v_add_f32_e32 v4, v13, v4
	v_add_f32_e32 v20, 1.0, v20
	v_rcp_f32_e32 v29, v20
	s_nop 0
	v_pk_mul_f32 v[20:21], v[28:29], v[26:27]
	v_lshlrev_b32_e32 v26, 16, v134
	v_pk_mul_f32 v[128:129], v[20:21], v[14:15]
	v_lshlrev_b32_e32 v20, 16, v22
	v_and_b32_e32 v21, 0xffff0000, v22
	v_and_b32_e32 v27, 0xffff0000, v134
	v_mul_f32_e32 v22, 0xbfb8aa3b, v26
	v_exp_f32_e32 v22, v22
	v_pk_fma_f32 v[16:17], v[24:25], v[20:21], v[16:17] op_sel_hi:[0,1,1]
	v_mul_f32_e32 v20, 0xbfb8aa3b, v27
	v_exp_f32_e32 v20, v20
	v_add_f32_e32 v22, 1.0, v22
	v_rcp_f32_e32 v28, v22
	v_lshlrev_b32_e32 v22, 16, v135
	v_add_f32_e32 v20, 1.0, v20
	v_rcp_f32_e32 v29, v20
	v_mul_f32_e32 v25, 0xbfb8aa3b, v22
	v_exp_f32_e32 v25, v25
	v_pk_mul_f32 v[14:15], v[128:129], v[128:129]
	v_pk_mul_f32 v[20:21], v[28:29], v[26:27]
	v_add_f32_e32 v4, v14, v4
	v_pk_mul_f32 v[132:133], v[20:21], v[16:17]
	v_lshlrev_b32_e32 v20, 16, v23
	v_and_b32_e32 v21, 0xffff0000, v23
	v_and_b32_e32 v23, 0xffff0000, v135
	v_add_f32_e32 v25, 1.0, v25
	v_pk_fma_f32 v[18:19], v[24:25], v[20:21], v[18:19] op_sel_hi:[0,1,1]
	v_mul_f32_e32 v20, 0xbfb8aa3b, v23
	v_exp_f32_e32 v20, v20
	v_rcp_f32_e32 v26, v25
	v_pk_mul_f32 v[16:17], v[132:133], v[132:133]
	v_add_f32_e32 v4, v15, v4
	v_add_f32_e32 v20, 1.0, v20
	v_rcp_f32_e32 v27, v20
	v_add_f32_e32 v4, v16, v4
	v_add_f32_e32 v4, v17, v4
	v_pk_mul_f32 v[20:21], v[26:27], v[22:23]
	s_nop 0
	v_pk_mul_f32 v[134:135], v[20:21], v[18:19]
	s_nop 0
	v_pk_mul_f32 v[18:19], v[134:135], v[134:135]
	s_nop 0
	v_add_f32_e32 v4, v18, v4
	v_add_f32_e32 v4, v19, v4
	ds_bpermute_b32 v5, v5, v4
	s_and_saveexec_b64 s[6:7], s[4:5]
	s_cbranch_execz .LBB0_1034
	s_waitcnt lgkmcnt(0)
	v_add_f32_e32 v4, v4, v5
	ds_write_b32 v161, v4
